# FSsmY gelu_tanh epilogue: constant chain folded (x*(C+C2*x^2) with v_fmaak), 3 fewer VALU per element, same f32 math kinds
# speedup vs baseline: 1.0199x; 1.0073x over previous
; #define GAS __attribute__((address_space(1)))
; __device__ __forceinline__ float fexp2(float x) { return __builtin_amdgcn_exp2f(x); }
; __device__ __forceinline__ float frcp(float x) { return __builtin_amdgcn_rcpf(x); }
; __device__ __forceinline__ float gelu_tanh(float x) { const float u = 0.7978845608028654f * (x + 0.044715f * x * x * x); return x * sigmoidf_(2.f * u); }
; __device__ __forceinline__ u32x4 pack8(f32x4 a, f32x4 b) { u32x4 w; w.x = pk2(a[0], a[1]); w.y = pk2(a[2], a[3]); w.z = pk2(b[0], b[1]); w.w = pk2(b[2], b[3]); return w; }
; __device__ __forceinline__ float sigmoidf_(float x) { return frcp(1.f + fexp2(-x * LOG2E)); }
; __device__ __forceinline__ float siluf_(float x) { return x * sigmoidf_(x); }
;     __device__ __forceinline__ void operator()(const Unit& u, int row, int col, f32x4 v0, f32x4 v1) const {
;         const int g = row >> 11, rowg = row & 2047, j = col >> 4, p = col & 15;
; #pragma unroll
;         for (int i = 0; i < 4; ++i) { v0[i] = gelu_tanh(v0[i]); v1[i] = gelu_tanh(v1[i]); }
;         *(GAS u32x4*)(Y + ((size_t)(rowg * 16 + j) * 512 + g * 16 + p)) = pack8(v0, v1);
.LBB0_699:
	v_mul_f32_e32 v156, 0xbdd2d3e8, v125
	v_fmaak_f32 v156, v125, v156, 0xc0135761
	v_mul_f32_e32 v156, v125, v156
	v_mul_f32_e32 v155, 0xbdd2d3e8, v120
	v_fmaak_f32 v155, v120, v155, 0xc0135761
	v_exp_f32_e32 v157, v156
	v_mul_f32_e32 v156, 0xbdd2d3e8, v121
	v_mul_f32_e32 v155, v120, v155
	v_fmaak_f32 v156, v121, v156, 0xc0135761
	v_mul_f32_e32 v156, v121, v156
	v_mul_f32_e32 v160, 0xbdd2d3e8, v127
	v_mul_f32_e32 v154, 0xbdd2d3e8, v124
	v_exp_f32_e32 v155, v155
	v_fmaak_f32 v160, v127, v160, 0xc0135761
	v_fmaak_f32 v154, v124, v154, 0xc0135761
	v_exp_f32_e32 v158, v156
	v_mul_f32_e32 v160, v127, v160
	v_mul_f32_e32 v154, v124, v154
	v_add_f32_e32 v155, 1.0, v155
	v_mul_f32_e32 v159, 0xbdd2d3e8, v122
	v_rcp_f32_e32 v156, v155
	v_add_f32_e32 v155, 1.0, v157
	v_add_f32_e32 v157, 1.0, v158
	v_mul_f32_e32 v158, 0xbdd2d3e8, v126
	v_fmaak_f32 v159, v122, v159, 0xc0135761
	v_exp_f32_e32 v161, v160
	v_mul_f32_e32 v160, 0xbdd2d3e8, v123
	v_exp_f32_e32 v154, v154
	v_fmaak_f32 v158, v126, v158, 0xc0135761
	v_mul_f32_e32 v159, v122, v159
	v_fmaak_f32 v160, v123, v160, 0xc0135761
	v_mul_f32_e32 v158, v126, v158
	v_mul_f32_e32 v160, v123, v160
	v_add_f32_e32 v154, 1.0, v154
	v_exp_f32_e32 v159, v159
	s_lshl_b32 s52, s72, 8
	v_rcp_f32_e32 v154, v154
	v_rcp_f32_e32 v155, v155
	v_exp_f32_e32 v158, v158
	v_exp_f32_e32 v162, v160
	s_add_i32 s52, s52, s85
	v_rcp_f32_e32 v157, v157
	v_or_b32_e32 v153, s52, v146
	v_lshlrev_b32_e32 v153, 4, v153
	v_add_f32_e32 v159, 1.0, v159
	v_and_b32_e32 v153, 0x7cf0, v153
	v_add_f32_e32 v158, 1.0, v158
	v_rcp_f32_e32 v160, v159
	v_add_f32_e32 v159, 1.0, v161
	v_add_f32_e32 v161, 1.0, v162
	v_pk_mul_f32 v[124:125], v[124:125], v[154:155]
	s_ashr_i32 s21, s52, 7
	v_rcp_f32_e32 v158, v158
	v_rcp_f32_e32 v159, v159
	v_rcp_f32_e32 v161, v161
	v_pk_mul_f32 v[154:155], v[120:121], v[156:157]
	v_cvt_pk_bf16_f32 v120, v124, v125
	v_add_u32_e32 v124, v153, v148
	s_and_b32 s50, s21, -16
	v_ashrrev_i32_e32 v125, 31, v124
	s_ashr_i32 s51, s50, 31
	v_lshlrev_b64 v[124:125], 10, v[124:125]
	v_lshl_add_u64 v[124:125], s[36:37], 0, v[124:125]
	s_lshl_b64 s[50:51], s[50:51], 1
	v_pk_mul_f32 v[126:127], v[126:127], v[158:159]
	v_pk_mul_f32 v[156:157], v[122:123], v[160:161]
	v_lshl_add_u64 v[124:125], v[124:125], 0, s[50:51]
	v_cvt_pk_bf16_f32 v121, v126, v127
	v_cvt_pk_bf16_f32 v122, v154, v155
	v_cvt_pk_bf16_f32 v123, v156, v157
	v_lshl_add_u64 v[124:125], v[124:125], 0, v[136:137]
	v_mul_f32_e32 v126, 0xbdd2d3e8, v116
	global_store_dwordx4 v[124:125], v[120:123], off
	v_fmaak_f32 v126, v116, v126, 0xc0135761
	v_mul_f32_e32 v126, v116, v126
	v_mul_f32_e32 v122, 0xbdd2d3e8, v117
	v_fmaak_f32 v122, v117, v122, 0xc0135761
	v_mul_f32_e32 v122, v117, v122
	v_mul_f32_e32 v127, 0xbdd2d3e8, v112
	v_exp_f32_e32 v126, v126
	v_fmaak_f32 v127, v112, v127, 0xc0135761
	v_exp_f32_e32 v123, v122
	v_mul_f32_e32 v122, 0xbdd2d3e8, v113
	v_mul_f32_e32 v127, v112, v127
	v_fmaak_f32 v122, v113, v122, 0xc0135761
	v_mul_f32_e32 v122, v113, v122
	v_add_f32_e32 v120, 1.0, v126
	v_mul_f32_e32 v126, 0xbdd2d3e8, v119
	v_exp_f32_e32 v127, v127
	v_fmaak_f32 v126, v119, v126, 0xc0135761
	v_exp_f32_e32 v124, v122
	v_mul_f32_e32 v126, v119, v126
	v_add_f32_e32 v121, 1.0, v127
	v_mul_f32_e32 v125, 0xbdd2d3e8, v114
	v_rcp_f32_e32 v122, v121
	v_add_f32_e32 v121, 1.0, v123
	v_add_f32_e32 v123, 1.0, v124
	v_mul_f32_e32 v124, 0xbdd2d3e8, v118
	v_fmaak_f32 v125, v114, v125, 0xc0135761
	v_exp_f32_e32 v127, v126
	v_mul_f32_e32 v126, 0xbdd2d3e8, v115
	v_fmaak_f32 v124, v118, v124, 0xc0135761
	v_mul_f32_e32 v125, v114, v125
	v_fmaak_f32 v126, v115, v126, 0xc0135761
	v_mul_f32_e32 v124, v118, v124
	v_mul_f32_e32 v126, v115, v126
	v_exp_f32_e32 v125, v125
	v_rcp_f32_e32 v120, v120
	v_rcp_f32_e32 v121, v121
	v_exp_f32_e32 v124, v124
	v_exp_f32_e32 v154, v126
	v_rcp_f32_e32 v123, v123
	v_add_f32_e32 v125, 1.0, v125
	v_add_f32_e32 v124, 1.0, v124
	v_rcp_f32_e32 v126, v125
	v_add_f32_e32 v125, 1.0, v127
	v_add_f32_e32 v127, 1.0, v154
	v_pk_mul_f32 v[116:117], v[116:117], v[120:121]
	v_rcp_f32_e32 v124, v124
	v_rcp_f32_e32 v125, v125
	v_rcp_f32_e32 v127, v127
	v_pk_mul_f32 v[120:121], v[112:113], v[122:123]
	v_cvt_pk_bf16_f32 v112, v116, v117
	v_add_u32_e32 v116, v153, v149
	v_ashrrev_i32_e32 v117, 31, v116
	v_lshlrev_b64 v[116:117], 10, v[116:117]
	v_lshl_add_u64 v[116:117], s[36:37], 0, v[116:117]
	v_pk_mul_f32 v[118:119], v[118:119], v[124:125]
	v_pk_mul_f32 v[122:123], v[114:115], v[126:127]
	v_lshl_add_u64 v[116:117], v[116:117], 0, s[50:51]
	v_cvt_pk_bf16_f32 v113, v118, v119
	v_cvt_pk_bf16_f32 v114, v120, v121
	v_cvt_pk_bf16_f32 v115, v122, v123
	v_lshl_add_u64 v[116:117], v[116:117], 0, v[136:137]
	global_store_dwordx4 v[116:117], v[112:115], off
	v_mul_f32_e32 v118, 0xbdd2d3e8, v111
	v_fmaak_f32 v118, v111, v118, 0xc0135761
	v_mul_f32_e32 v114, 0xbdd2d3e8, v109
	v_fmaak_f32 v114, v109, v114, 0xc0135761
	v_mul_f32_e32 v114, v109, v114
	v_mul_f32_e32 v113, 0xbdd2d3e8, v104
	v_fmaak_f32 v113, v104, v113, 0xc0135761
	v_exp_f32_e32 v115, v114
	v_mul_f32_e32 v114, 0xbdd2d3e8, v105
	v_mul_f32_e32 v113, v104, v113
	v_fmaak_f32 v114, v105, v114, 0xc0135761
	v_mul_f32_e32 v114, v105, v114
	v_mul_f32_e32 v112, 0xbdd2d3e8, v108
	v_exp_f32_e32 v113, v113
	v_fmaak_f32 v112, v108, v112, 0xc0135761
	v_exp_f32_e32 v116, v114
	v_mul_f32_e32 v118, v111, v118
	v_mul_f32_e32 v112, v108, v112
	v_add_f32_e32 v113, 1.0, v113
	v_mul_f32_e32 v117, 0xbdd2d3e8, v106
	v_rcp_f32_e32 v114, v113
	v_add_f32_e32 v113, 1.0, v115
	v_add_f32_e32 v115, 1.0, v116
	v_mul_f32_e32 v116, 0xbdd2d3e8, v110
	v_fmaak_f32 v117, v106, v117, 0xc0135761
	v_exp_f32_e32 v119, v118
	v_mul_f32_e32 v118, 0xbdd2d3e8, v107
; #define GAS __attribute__((address_space(1)))
; __device__ __forceinline__ float fexp2(float x) { return __builtin_amdgcn_exp2f(x); }
; __device__ __forceinline__ float frcp(float x) { return __builtin_amdgcn_rcpf(x); }
; __device__ __forceinline__ float gelu_tanh(float x) { const float u = 0.7978845608028654f * (x + 0.044715f * x * x * x); return x * sigmoidf_(2.f * u); }
; __device__ __forceinline__ u32x4 pack8(f32x4 a, f32x4 b) { u32x4 w; w.x = pk2(a[0], a[1]); w.y = pk2(a[2], a[3]); w.z = pk2(b[0], b[1]); w.w = pk2(b[2], b[3]); return w; }
; __device__ __forceinline__ float sigmoidf_(float x) { return frcp(1.f + fexp2(-x * LOG2E)); }
; __device__ __forceinline__ float siluf_(float x) { return x * sigmoidf_(x); }
;     __device__ __forceinline__ void operator()(const Unit& u, int row, int col, f32x4 v0, f32x4 v1) const {
;         const int g = row >> 11, rowg = row & 2047, j = col >> 4, p = col & 15;
; #pragma unroll
;         for (int i = 0; i < 4; ++i) { v0[i] = gelu_tanh(v0[i]); v1[i] = gelu_tanh(v1[i]); }
;         *(GAS u32x4*)(Y + ((size_t)(rowg * 16 + j) * 512 + g * 16 + p)) = pack8(v0, v1);
	v_exp_f32_e32 v112, v112
	v_fmaak_f32 v116, v110, v116, 0xc0135761
	v_mul_f32_e32 v117, v106, v117
	v_fmaak_f32 v118, v107, v118, 0xc0135761
	v_mul_f32_e32 v116, v110, v116
	v_mul_f32_e32 v118, v107, v118
	v_add_f32_e32 v112, 1.0, v112
	v_exp_f32_e32 v117, v117
	v_rcp_f32_e32 v112, v112
	v_rcp_f32_e32 v113, v113
	v_exp_f32_e32 v116, v116
	v_exp_f32_e32 v121, v118
	v_rcp_f32_e32 v115, v115
	v_add_f32_e32 v117, 1.0, v117
	v_or_b32_e32 v120, 0x100, v153
	v_add_f32_e32 v116, 1.0, v116
	v_rcp_f32_e32 v118, v117
	v_add_f32_e32 v117, 1.0, v119
	v_add_f32_e32 v119, 1.0, v121
	v_pk_mul_f32 v[108:109], v[108:109], v[112:113]
	v_rcp_f32_e32 v116, v116
	v_rcp_f32_e32 v117, v117
	v_rcp_f32_e32 v119, v119
	v_pk_mul_f32 v[112:113], v[104:105], v[114:115]
	v_cvt_pk_bf16_f32 v104, v108, v109
	v_add_u32_e32 v108, v120, v148
	v_ashrrev_i32_e32 v109, 31, v108
	v_lshlrev_b64 v[108:109], 10, v[108:109]
	v_lshl_add_u64 v[108:109], s[36:37], 0, v[108:109]
	v_pk_mul_f32 v[110:111], v[110:111], v[116:117]
	v_pk_mul_f32 v[114:115], v[106:107], v[118:119]
	v_lshl_add_u64 v[108:109], v[108:109], 0, s[50:51]
	v_cvt_pk_bf16_f32 v105, v110, v111
	v_cvt_pk_bf16_f32 v106, v112, v113
	v_cvt_pk_bf16_f32 v107, v114, v115
	v_lshl_add_u64 v[108:109], v[108:109], 0, v[136:137]
	v_mul_f32_e32 v110, 0xbdd2d3e8, v100
	global_store_dwordx4 v[108:109], v[104:107], off
	v_fmaak_f32 v110, v100, v110, 0xc0135761
	v_mul_f32_e32 v110, v100, v110
	v_mul_f32_e32 v106, 0xbdd2d3e8, v101
	v_fmaak_f32 v106, v101, v106, 0xc0135761
	v_mul_f32_e32 v106, v101, v106
	v_mul_f32_e32 v111, 0xbdd2d3e8, v96
	v_exp_f32_e32 v110, v110
	v_fmaak_f32 v111, v96, v111, 0xc0135761
	v_exp_f32_e32 v107, v106
	v_mul_f32_e32 v106, 0xbdd2d3e8, v97
	v_mul_f32_e32 v111, v96, v111
	v_fmaak_f32 v106, v97, v106, 0xc0135761
	v_mul_f32_e32 v106, v97, v106
	v_add_f32_e32 v104, 1.0, v110
	v_mul_f32_e32 v110, 0xbdd2d3e8, v103
	v_exp_f32_e32 v111, v111
	v_fmaak_f32 v110, v103, v110, 0xc0135761
	v_exp_f32_e32 v108, v106
	v_mul_f32_e32 v110, v103, v110
	v_add_f32_e32 v105, 1.0, v111
	v_mul_f32_e32 v109, 0xbdd2d3e8, v98
	v_rcp_f32_e32 v106, v105
	v_add_f32_e32 v105, 1.0, v107
	v_add_f32_e32 v107, 1.0, v108
	v_mul_f32_e32 v108, 0xbdd2d3e8, v102
	v_fmaak_f32 v109, v98, v109, 0xc0135761
	v_exp_f32_e32 v111, v110
	v_mul_f32_e32 v110, 0xbdd2d3e8, v99
	v_fmaak_f32 v108, v102, v108, 0xc0135761
	v_mul_f32_e32 v109, v98, v109
	v_fmaak_f32 v110, v99, v110, 0xc0135761
	v_mul_f32_e32 v108, v102, v108
	v_mul_f32_e32 v110, v99, v110
	v_exp_f32_e32 v109, v109
	v_rcp_f32_e32 v104, v104
	v_rcp_f32_e32 v105, v105
	v_exp_f32_e32 v108, v108
	v_exp_f32_e32 v112, v110
	v_rcp_f32_e32 v107, v107
	v_add_f32_e32 v109, 1.0, v109
	v_add_f32_e32 v108, 1.0, v108
	v_rcp_f32_e32 v110, v109
	v_add_f32_e32 v109, 1.0, v111
	v_add_f32_e32 v111, 1.0, v112
	v_pk_mul_f32 v[100:101], v[100:101], v[104:105]
	v_rcp_f32_e32 v108, v108
	v_rcp_f32_e32 v109, v109
	v_rcp_f32_e32 v111, v111
	v_pk_mul_f32 v[104:105], v[96:97], v[106:107]
	v_cvt_pk_bf16_f32 v96, v100, v101
	v_add_u32_e32 v100, v120, v149
	v_ashrrev_i32_e32 v101, 31, v100
	v_lshlrev_b64 v[100:101], 10, v[100:101]
	v_lshl_add_u64 v[100:101], s[36:37], 0, v[100:101]
	v_pk_mul_f32 v[102:103], v[102:103], v[108:109]
	v_pk_mul_f32 v[106:107], v[98:99], v[110:111]
	v_lshl_add_u64 v[100:101], v[100:101], 0, s[50:51]
	v_cvt_pk_bf16_f32 v97, v102, v103
	v_cvt_pk_bf16_f32 v98, v104, v105
	v_cvt_pk_bf16_f32 v99, v106, v107
	v_lshl_add_u64 v[100:101], v[100:101], 0, v[136:137]
	global_store_dwordx4 v[100:101], v[96:99], off
	v_mul_f32_e32 v102, 0xbdd2d3e8, v95
	v_fmaak_f32 v102, v95, v102, 0xc0135761
	v_mul_f32_e32 v98, 0xbdd2d3e8, v93
	v_fmaak_f32 v98, v93, v98, 0xc0135761
	v_mul_f32_e32 v98, v93, v98
	v_mul_f32_e32 v97, 0xbdd2d3e8, v88
	v_fmaak_f32 v97, v88, v97, 0xc0135761
	v_exp_f32_e32 v99, v98
	v_mul_f32_e32 v98, 0xbdd2d3e8, v89
	v_mul_f32_e32 v97, v88, v97
	v_fmaak_f32 v98, v89, v98, 0xc0135761
	v_mul_f32_e32 v98, v89, v98
	v_mul_f32_e32 v96, 0xbdd2d3e8, v92
	v_exp_f32_e32 v97, v97
	v_fmaak_f32 v96, v92, v96, 0xc0135761
	v_exp_f32_e32 v100, v98
	v_mul_f32_e32 v102, v95, v102
	v_mul_f32_e32 v96, v92, v96
	v_add_f32_e32 v97, 1.0, v97
	v_mul_f32_e32 v101, 0xbdd2d3e8, v90
	v_rcp_f32_e32 v98, v97
	v_add_f32_e32 v97, 1.0, v99
	v_add_f32_e32 v99, 1.0, v100
	v_mul_f32_e32 v100, 0xbdd2d3e8, v94
	v_fmaak_f32 v101, v90, v101, 0xc0135761
	v_exp_f32_e32 v103, v102
	v_mul_f32_e32 v102, 0xbdd2d3e8, v91
	v_exp_f32_e32 v96, v96
	v_fmaak_f32 v100, v94, v100, 0xc0135761
	v_mul_f32_e32 v101, v90, v101
	v_fmaak_f32 v102, v91, v102, 0xc0135761
	v_mul_f32_e32 v100, v94, v100
	v_mul_f32_e32 v102, v91, v102
	v_add_f32_e32 v96, 1.0, v96
	v_exp_f32_e32 v101, v101
	v_rcp_f32_e32 v96, v96
	v_rcp_f32_e32 v97, v97
	v_exp_f32_e32 v100, v100
	v_exp_f32_e32 v105, v102
	v_rcp_f32_e32 v99, v99
	v_add_f32_e32 v101, 1.0, v101
	v_or_b32_e32 v104, 0x200, v153
	v_add_f32_e32 v100, 1.0, v100
	v_rcp_f32_e32 v102, v101
	v_add_f32_e32 v101, 1.0, v103
	v_add_f32_e32 v103, 1.0, v105
	v_pk_mul_f32 v[92:93], v[92:93], v[96:97]
	v_rcp_f32_e32 v100, v100
	v_rcp_f32_e32 v101, v101
	v_rcp_f32_e32 v103, v103
	v_pk_mul_f32 v[96:97], v[88:89], v[98:99]
	v_cvt_pk_bf16_f32 v88, v92, v93
	v_add_u32_e32 v92, v104, v148
	v_ashrrev_i32_e32 v93, 31, v92
	v_lshlrev_b64 v[92:93], 10, v[92:93]
	v_lshl_add_u64 v[92:93], s[36:37], 0, v[92:93]
	v_pk_mul_f32 v[94:95], v[94:95], v[100:101]
	v_pk_mul_f32 v[98:99], v[90:91], v[102:103]
	v_lshl_add_u64 v[92:93], v[92:93], 0, s[50:51]
	v_cvt_pk_bf16_f32 v89, v94, v95
	v_cvt_pk_bf16_f32 v90, v96, v97
	v_cvt_pk_bf16_f32 v91, v98, v99
	v_lshl_add_u64 v[92:93], v[92:93], 0, v[136:137]
	v_mul_f32_e32 v94, 0xbdd2d3e8, v84
; #define GAS __attribute__((address_space(1)))
; __device__ __forceinline__ float fexp2(float x) { return __builtin_amdgcn_exp2f(x); }
; __device__ __forceinline__ float frcp(float x) { return __builtin_amdgcn_rcpf(x); }
; __device__ __forceinline__ float gelu_tanh(float x) { const float u = 0.7978845608028654f * (x + 0.044715f * x * x * x); return x * sigmoidf_(2.f * u); }
; __device__ __forceinline__ u32x4 pack8(f32x4 a, f32x4 b) { u32x4 w; w.x = pk2(a[0], a[1]); w.y = pk2(a[2], a[3]); w.z = pk2(b[0], b[1]); w.w = pk2(b[2], b[3]); return w; }
; __device__ __forceinline__ float sigmoidf_(float x) { return frcp(1.f + fexp2(-x * LOG2E)); }
; __device__ __forceinline__ float siluf_(float x) { return x * sigmoidf_(x); }
;     __device__ __forceinline__ void operator()(const Unit& u, int row, int col, f32x4 v0, f32x4 v1) const {
;         const int g = row >> 11, rowg = row & 2047, j = col >> 4, p = col & 15;
; #pragma unroll
;         for (int i = 0; i < 4; ++i) { v0[i] = gelu_tanh(v0[i]); v1[i] = gelu_tanh(v1[i]); }
;         *(GAS u32x4*)(Y + ((size_t)(rowg * 16 + j) * 512 + g * 16 + p)) = pack8(v0, v1);
	global_store_dwordx4 v[92:93], v[88:91], off
	v_fmaak_f32 v94, v84, v94, 0xc0135761
	v_mul_f32_e32 v94, v84, v94
	v_mul_f32_e32 v90, 0xbdd2d3e8, v85
	v_fmaak_f32 v90, v85, v90, 0xc0135761
	v_mul_f32_e32 v90, v85, v90
	v_mul_f32_e32 v95, 0xbdd2d3e8, v80
	v_exp_f32_e32 v94, v94
	v_fmaak_f32 v95, v80, v95, 0xc0135761
	v_exp_f32_e32 v91, v90
	v_mul_f32_e32 v90, 0xbdd2d3e8, v81
	v_mul_f32_e32 v95, v80, v95
	v_fmaak_f32 v90, v81, v90, 0xc0135761
	v_mul_f32_e32 v90, v81, v90
	v_add_f32_e32 v88, 1.0, v94
	v_mul_f32_e32 v94, 0xbdd2d3e8, v87
	v_exp_f32_e32 v95, v95
	v_fmaak_f32 v94, v87, v94, 0xc0135761
	v_exp_f32_e32 v92, v90
	v_mul_f32_e32 v94, v87, v94
	v_add_f32_e32 v89, 1.0, v95
	v_mul_f32_e32 v93, 0xbdd2d3e8, v82
	v_rcp_f32_e32 v90, v89
	v_add_f32_e32 v89, 1.0, v91
	v_add_f32_e32 v91, 1.0, v92
	v_mul_f32_e32 v92, 0xbdd2d3e8, v86
	v_fmaak_f32 v93, v82, v93, 0xc0135761
	v_exp_f32_e32 v95, v94
	v_mul_f32_e32 v94, 0xbdd2d3e8, v83
	v_fmaak_f32 v92, v86, v92, 0xc0135761
	v_mul_f32_e32 v93, v82, v93
	v_fmaak_f32 v94, v83, v94, 0xc0135761
	v_mul_f32_e32 v92, v86, v92
	v_mul_f32_e32 v94, v83, v94
	v_exp_f32_e32 v93, v93
	v_rcp_f32_e32 v88, v88
	v_rcp_f32_e32 v89, v89
	v_exp_f32_e32 v92, v92
	v_exp_f32_e32 v96, v94
	v_rcp_f32_e32 v91, v91
	v_add_f32_e32 v93, 1.0, v93
	v_add_f32_e32 v92, 1.0, v92
	v_rcp_f32_e32 v94, v93
	v_add_f32_e32 v93, 1.0, v95
	v_add_f32_e32 v95, 1.0, v96
	v_pk_mul_f32 v[84:85], v[84:85], v[88:89]
	v_rcp_f32_e32 v92, v92
	v_rcp_f32_e32 v93, v93
	v_rcp_f32_e32 v95, v95
	v_pk_mul_f32 v[88:89], v[80:81], v[90:91]
	v_cvt_pk_bf16_f32 v80, v84, v85
	v_add_u32_e32 v84, v104, v149
	v_ashrrev_i32_e32 v85, 31, v84
	v_lshlrev_b64 v[84:85], 10, v[84:85]
	v_lshl_add_u64 v[84:85], s[36:37], 0, v[84:85]
	v_pk_mul_f32 v[86:87], v[86:87], v[92:93]
	v_pk_mul_f32 v[90:91], v[82:83], v[94:95]
	v_lshl_add_u64 v[84:85], v[84:85], 0, s[50:51]
	v_cvt_pk_bf16_f32 v81, v86, v87
	v_cvt_pk_bf16_f32 v82, v88, v89
	v_cvt_pk_bf16_f32 v83, v90, v91
	v_lshl_add_u64 v[84:85], v[84:85], 0, v[136:137]
	global_store_dwordx4 v[84:85], v[80:83], off
	v_mul_f32_e32 v86, 0xbdd2d3e8, v79
	v_fmaak_f32 v86, v79, v86, 0xc0135761
	v_mul_f32_e32 v82, 0xbdd2d3e8, v77
	v_fmaak_f32 v82, v77, v82, 0xc0135761
	v_mul_f32_e32 v82, v77, v82
	v_mul_f32_e32 v81, 0xbdd2d3e8, v72
	v_fmaak_f32 v81, v72, v81, 0xc0135761
	v_exp_f32_e32 v83, v82
	v_mul_f32_e32 v82, 0xbdd2d3e8, v73
	v_mul_f32_e32 v81, v72, v81
	v_fmaak_f32 v82, v73, v82, 0xc0135761
	v_mul_f32_e32 v82, v73, v82
	v_mul_f32_e32 v80, 0xbdd2d3e8, v76
	v_exp_f32_e32 v81, v81
	v_fmaak_f32 v80, v76, v80, 0xc0135761
	v_exp_f32_e32 v84, v82
	v_mul_f32_e32 v86, v79, v86
	v_mul_f32_e32 v80, v76, v80
	v_add_f32_e32 v81, 1.0, v81
	v_mul_f32_e32 v85, 0xbdd2d3e8, v74
	v_rcp_f32_e32 v82, v81
	v_add_f32_e32 v81, 1.0, v83
	v_add_f32_e32 v83, 1.0, v84
	v_mul_f32_e32 v84, 0xbdd2d3e8, v78
	v_fmaak_f32 v85, v74, v85, 0xc0135761
	v_exp_f32_e32 v87, v86
	v_mul_f32_e32 v86, 0xbdd2d3e8, v75
	v_exp_f32_e32 v80, v80
	v_fmaak_f32 v84, v78, v84, 0xc0135761
	v_mul_f32_e32 v85, v74, v85
	v_fmaak_f32 v86, v75, v86, 0xc0135761
	v_mul_f32_e32 v84, v78, v84
	v_mul_f32_e32 v86, v75, v86
	v_add_f32_e32 v80, 1.0, v80
	v_exp_f32_e32 v85, v85
	v_rcp_f32_e32 v80, v80
	v_rcp_f32_e32 v81, v81
	v_exp_f32_e32 v84, v84
	v_exp_f32_e32 v89, v86
	v_rcp_f32_e32 v83, v83
	v_add_f32_e32 v85, 1.0, v85
	v_or_b32_e32 v88, 0x300, v153
	v_add_f32_e32 v84, 1.0, v84
	v_rcp_f32_e32 v86, v85
	v_add_f32_e32 v85, 1.0, v87
	v_add_f32_e32 v87, 1.0, v89
	v_pk_mul_f32 v[76:77], v[76:77], v[80:81]
	v_rcp_f32_e32 v84, v84
	v_rcp_f32_e32 v85, v85
	v_rcp_f32_e32 v87, v87
	v_pk_mul_f32 v[80:81], v[72:73], v[82:83]
	v_cvt_pk_bf16_f32 v72, v76, v77
	v_add_u32_e32 v76, v88, v148
	v_ashrrev_i32_e32 v77, 31, v76
	v_lshlrev_b64 v[76:77], 10, v[76:77]
	v_lshl_add_u64 v[76:77], s[36:37], 0, v[76:77]
	v_pk_mul_f32 v[78:79], v[78:79], v[84:85]
	v_pk_mul_f32 v[82:83], v[74:75], v[86:87]
	v_lshl_add_u64 v[76:77], v[76:77], 0, s[50:51]
	v_cvt_pk_bf16_f32 v73, v78, v79
	v_cvt_pk_bf16_f32 v74, v80, v81
	v_cvt_pk_bf16_f32 v75, v82, v83
	v_lshl_add_u64 v[76:77], v[76:77], 0, v[136:137]
	v_mul_f32_e32 v78, 0xbdd2d3e8, v68
	global_store_dwordx4 v[76:77], v[72:75], off
	v_fmaak_f32 v78, v68, v78, 0xc0135761
	v_mul_f32_e32 v78, v68, v78
	v_mul_f32_e32 v74, 0xbdd2d3e8, v69
	v_fmaak_f32 v74, v69, v74, 0xc0135761
	v_mul_f32_e32 v74, v69, v74
	v_mul_f32_e32 v79, 0xbdd2d3e8, v64
	v_exp_f32_e32 v78, v78
	v_fmaak_f32 v79, v64, v79, 0xc0135761
	v_exp_f32_e32 v75, v74
	v_mul_f32_e32 v74, 0xbdd2d3e8, v65
	v_mul_f32_e32 v79, v64, v79
	v_fmaak_f32 v74, v65, v74, 0xc0135761
	v_mul_f32_e32 v74, v65, v74
	v_add_f32_e32 v72, 1.0, v78
	v_mul_f32_e32 v78, 0xbdd2d3e8, v71
	v_exp_f32_e32 v79, v79
	v_fmaak_f32 v78, v71, v78, 0xc0135761
	v_exp_f32_e32 v76, v74
	v_mul_f32_e32 v78, v71, v78
	v_add_f32_e32 v73, 1.0, v79
	v_mul_f32_e32 v77, 0xbdd2d3e8, v66
	v_rcp_f32_e32 v74, v73
	v_add_f32_e32 v73, 1.0, v75
	v_add_f32_e32 v75, 1.0, v76
	v_mul_f32_e32 v76, 0xbdd2d3e8, v70
	v_fmaak_f32 v77, v66, v77, 0xc0135761
	v_exp_f32_e32 v79, v78
	v_mul_f32_e32 v78, 0xbdd2d3e8, v67
	v_fmaak_f32 v76, v70, v76, 0xc0135761
	v_mul_f32_e32 v77, v66, v77
	v_fmaak_f32 v78, v67, v78, 0xc0135761
	v_mul_f32_e32 v76, v70, v76
	v_mul_f32_e32 v78, v67, v78
	v_exp_f32_e32 v77, v77
	v_rcp_f32_e32 v72, v72
	v_rcp_f32_e32 v73, v73
	v_exp_f32_e32 v76, v76
	v_exp_f32_e32 v80, v78
	v_rcp_f32_e32 v75, v75
	v_add_f32_e32 v77, 1.0, v77
	v_add_f32_e32 v76, 1.0, v76
	v_rcp_f32_e32 v78, v77
	v_add_f32_e32 v77, 1.0, v79
	v_add_f32_e32 v79, 1.0, v80
	v_pk_mul_f32 v[68:69], v[68:69], v[72:73]
	v_rcp_f32_e32 v76, v76
	v_rcp_f32_e32 v77, v77
	v_rcp_f32_e32 v79, v79
; #define GAS __attribute__((address_space(1)))
; __device__ __forceinline__ float gelu_tanh(float x) { const float u = 0.7978845608028654f * (x + 0.044715f * x * x * x); return x * sigmoidf_(2.f * u); }
; __device__ __forceinline__ u32x4 pack8(f32x4 a, f32x4 b) { u32x4 w; w.x = pk2(a[0], a[1]); w.y = pk2(a[2], a[3]); w.z = pk2(b[0], b[1]); w.w = pk2(b[2], b[3]); return w; }
;     __device__ __forceinline__ void operator()(const f32x4 (&acc)[2][2][4][2], const Unit& u, int wr, int wc, int fr, int fq) const {
;     ...
; #pragma unroll
;             for (int m = 0; m < 4; ++m) {
;                 const int row = u.pm * BM + ai * HALF + wr * 64 + m * 16 + fr;
; #pragma unroll
;                 for (int bj = 0; bj < 2; ++bj) f(u, row, bj * HALF + wc * 32 + 8 * fq, acc[ai][bj][m][0], acc[ai][bj][m][1]);
;             }
;     __device__ __forceinline__ void operator()(const Unit& u, int row, int col, f32x4 v0, f32x4 v1) const {
;         const int g = row >> 11, rowg = row & 2047, j = col >> 4, p = col & 15;
; #pragma unroll
;         for (int i = 0; i < 4; ++i) { v0[i] = gelu_tanh(v0[i]); v1[i] = gelu_tanh(v1[i]); }
;         *(GAS u32x4*)(Y + ((size_t)(rowg * 16 + j) * 512 + g * 16 + p)) = pack8(v0, v1);
	v_pk_mul_f32 v[72:73], v[64:65], v[74:75]
	v_cvt_pk_bf16_f32 v64, v68, v69
	v_add_u32_e32 v68, v88, v149
	v_ashrrev_i32_e32 v69, 31, v68
	v_lshlrev_b64 v[68:69], 10, v[68:69]
	v_lshl_add_u64 v[68:69], s[36:37], 0, v[68:69]
	v_pk_mul_f32 v[70:71], v[70:71], v[76:77]
	v_pk_mul_f32 v[74:75], v[66:67], v[78:79]
	v_lshl_add_u64 v[68:69], v[68:69], 0, s[50:51]
	v_cvt_pk_bf16_f32 v65, v70, v71
	v_cvt_pk_bf16_f32 v66, v72, v73
	v_cvt_pk_bf16_f32 v67, v74, v75
	v_lshl_add_u64 v[68:69], v[68:69], 0, v[136:137]
	global_store_dwordx4 v[68:69], v[64:67], off
	v_mul_f32_e32 v68, 0xbdd2d3e8, v57
	v_fmaak_f32 v68, v57, v68, 0xc0135761
	v_mul_f32_e32 v65, 0xbdd2d3e8, v60
	v_fmaak_f32 v65, v60, v65, 0xc0135761
	v_mul_f32_e32 v66, 0xbdd2d3e8, v56
	v_mul_f32_e32 v65, v60, v65
	v_fmaak_f32 v66, v56, v66, 0xc0135761
	v_mul_f32_e32 v66, v56, v66
	v_exp_f32_e32 v65, v65
	v_exp_f32_e32 v67, v66
	v_mul_f32_e32 v68, v57, v68
	v_add_f32_e32 v65, 1.0, v65
	v_rcp_f32_e32 v66, v65
	v_add_f32_e32 v65, 1.0, v67
	v_mul_f32_e32 v67, 0xbdd2d3e8, v61
	v_fmaak_f32 v67, v61, v67, 0xc0135761
	v_mul_f32_e32 v67, v61, v67
	v_exp_f32_e32 v67, v67
	v_exp_f32_e32 v69, v68
	v_rcp_f32_e32 v68, v65
	v_add_f32_e32 v65, 1.0, v67
	v_rcp_f32_e32 v67, v65
	v_add_f32_e32 v65, 1.0, v69
	v_mul_f32_e32 v69, 0xbdd2d3e8, v62
	v_fmaak_f32 v69, v62, v69, 0xc0135761
	v_mul_f32_e32 v69, v62, v69
	v_exp_f32_e32 v70, v69
	v_mul_f32_e32 v69, 0xbdd2d3e8, v58
	v_fmaak_f32 v69, v58, v69, 0xc0135761
	v_mul_f32_e32 v69, v58, v69
	v_exp_f32_e32 v71, v69
	v_rcp_f32_e32 v69, v65
	v_add_f32_e32 v65, 1.0, v70
	v_rcp_f32_e32 v70, v65
	v_add_f32_e32 v65, 1.0, v71
	v_mul_f32_e32 v71, 0xbdd2d3e8, v63
	v_fmaak_f32 v71, v63, v71, 0xc0135761
	v_mul_f32_e32 v72, 0xbdd2d3e8, v59
	v_mul_f32_e32 v71, v63, v71
	v_fmaak_f32 v72, v59, v72, 0xc0135761
	v_mul_f32_e32 v72, v59, v72
	v_exp_f32_e32 v71, v71
	v_exp_f32_e32 v73, v72
	s_addk_i32 s52, 0x80
	v_or_b32_e32 v64, s52, v146
	v_lshlrev_b32_e32 v64, 4, v64
	v_rcp_f32_e32 v72, v65
	v_add_f32_e32 v65, 1.0, v71
	v_and_b32_e32 v64, 0x7cf0, v64
	v_rcp_f32_e32 v71, v65
	v_add_f32_e32 v65, 1.0, v73
	v_pk_mul_f32 v[60:61], v[60:61], v[66:67]
	s_ashr_i32 s21, s52, 7
	v_rcp_f32_e32 v73, v65
	v_pk_mul_f32 v[66:67], v[56:57], v[68:69]
	v_cvt_pk_bf16_f32 v56, v60, v61
	v_add_u32_e32 v60, v64, v148
	s_and_b32 s50, s21, -16
	v_ashrrev_i32_e32 v61, 31, v60
	s_ashr_i32 s51, s50, 31
	v_lshlrev_b64 v[60:61], 10, v[60:61]
	v_lshl_add_u64 v[60:61], s[36:37], 0, v[60:61]
	s_lshl_b64 s[50:51], s[50:51], 1
	v_pk_mul_f32 v[62:63], v[62:63], v[70:71]
	v_pk_mul_f32 v[68:69], v[58:59], v[72:73]
	v_lshl_add_u64 v[60:61], v[60:61], 0, s[50:51]
	v_cvt_pk_bf16_f32 v57, v62, v63
	v_cvt_pk_bf16_f32 v58, v66, v67
	v_cvt_pk_bf16_f32 v59, v68, v69
	v_lshl_add_u64 v[60:61], v[60:61], 0, v[136:137]
	v_mul_f32_e32 v62, 0xbdd2d3e8, v52
	global_store_dwordx4 v[60:61], v[56:59], off
	v_fmaak_f32 v62, v52, v62, 0xc0135761
	v_mul_f32_e32 v62, v52, v62
	v_mul_f32_e32 v58, 0xbdd2d3e8, v53
	v_fmaak_f32 v58, v53, v58, 0xc0135761
	v_mul_f32_e32 v58, v53, v58
	v_mul_f32_e32 v63, 0xbdd2d3e8, v48
	v_exp_f32_e32 v62, v62
	v_fmaak_f32 v63, v48, v63, 0xc0135761
	v_exp_f32_e32 v59, v58
	v_mul_f32_e32 v58, 0xbdd2d3e8, v49
	v_mul_f32_e32 v63, v48, v63
	v_fmaak_f32 v58, v49, v58, 0xc0135761
	v_mul_f32_e32 v58, v49, v58
	v_add_f32_e32 v56, 1.0, v62
	v_mul_f32_e32 v62, 0xbdd2d3e8, v55
	v_exp_f32_e32 v63, v63
	v_fmaak_f32 v62, v55, v62, 0xc0135761
	v_exp_f32_e32 v60, v58
	v_mul_f32_e32 v62, v55, v62
	v_add_f32_e32 v57, 1.0, v63
	v_mul_f32_e32 v61, 0xbdd2d3e8, v50
	v_rcp_f32_e32 v58, v57
	v_add_f32_e32 v57, 1.0, v59
	v_add_f32_e32 v59, 1.0, v60
	v_mul_f32_e32 v60, 0xbdd2d3e8, v54
	v_fmaak_f32 v61, v50, v61, 0xc0135761
	v_exp_f32_e32 v63, v62
	v_mul_f32_e32 v62, 0xbdd2d3e8, v51
	v_fmaak_f32 v60, v54, v60, 0xc0135761
	v_mul_f32_e32 v61, v50, v61
	v_fmaak_f32 v62, v51, v62, 0xc0135761
	v_mul_f32_e32 v60, v54, v60
	v_mul_f32_e32 v62, v51, v62
	v_exp_f32_e32 v61, v61
	v_rcp_f32_e32 v56, v56
	v_rcp_f32_e32 v57, v57
	v_exp_f32_e32 v60, v60
	v_exp_f32_e32 v65, v62
	v_rcp_f32_e32 v59, v59
	v_add_f32_e32 v61, 1.0, v61
	v_add_f32_e32 v60, 1.0, v60
	v_rcp_f32_e32 v62, v61
	v_add_f32_e32 v61, 1.0, v63
	v_add_f32_e32 v63, 1.0, v65
	v_pk_mul_f32 v[52:53], v[52:53], v[56:57]
	v_rcp_f32_e32 v60, v60
	v_rcp_f32_e32 v61, v61
	v_rcp_f32_e32 v63, v63
	v_pk_mul_f32 v[56:57], v[48:49], v[58:59]
	v_cvt_pk_bf16_f32 v48, v52, v53
	v_add_u32_e32 v52, v64, v149
	v_ashrrev_i32_e32 v53, 31, v52
	v_lshlrev_b64 v[52:53], 10, v[52:53]
	v_lshl_add_u64 v[52:53], s[36:37], 0, v[52:53]
	v_pk_mul_f32 v[54:55], v[54:55], v[60:61]
	v_pk_mul_f32 v[58:59], v[50:51], v[62:63]
	v_lshl_add_u64 v[52:53], v[52:53], 0, s[50:51]
	v_cvt_pk_bf16_f32 v49, v54, v55
	v_cvt_pk_bf16_f32 v50, v56, v57
	v_cvt_pk_bf16_f32 v51, v58, v59
	v_lshl_add_u64 v[52:53], v[52:53], 0, v[136:137]
	global_store_dwordx4 v[52:53], v[48:51], off
	v_mul_f32_e32 v54, 0xbdd2d3e8, v47
	v_fmaak_f32 v54, v47, v54, 0xc0135761
	v_mul_f32_e32 v50, 0xbdd2d3e8, v45
	v_fmaak_f32 v50, v45, v50, 0xc0135761
	v_mul_f32_e32 v50, v45, v50
	v_mul_f32_e32 v49, 0xbdd2d3e8, v40
	v_fmaak_f32 v49, v40, v49, 0xc0135761
	v_exp_f32_e32 v51, v50
	v_mul_f32_e32 v50, 0xbdd2d3e8, v41
	v_mul_f32_e32 v49, v40, v49
	v_fmaak_f32 v50, v41, v50, 0xc0135761
	v_mul_f32_e32 v50, v41, v50
	v_mul_f32_e32 v48, 0xbdd2d3e8, v44
	v_exp_f32_e32 v49, v49
	v_fmaak_f32 v48, v44, v48, 0xc0135761
	v_exp_f32_e32 v52, v50
	v_mul_f32_e32 v54, v47, v54
	v_mul_f32_e32 v48, v44, v48
	v_add_f32_e32 v49, 1.0, v49
	v_mul_f32_e32 v53, 0xbdd2d3e8, v42
	v_rcp_f32_e32 v50, v49
	v_add_f32_e32 v49, 1.0, v51
	v_add_f32_e32 v51, 1.0, v52
	v_mul_f32_e32 v52, 0xbdd2d3e8, v46
; #define GAS __attribute__((address_space(1)))
; __device__ __forceinline__ float fexp2(float x) { return __builtin_amdgcn_exp2f(x); }
; __device__ __forceinline__ float frcp(float x) { return __builtin_amdgcn_rcpf(x); }
; __device__ __forceinline__ float gelu_tanh(float x) { const float u = 0.7978845608028654f * (x + 0.044715f * x * x * x); return x * sigmoidf_(2.f * u); }
; __device__ __forceinline__ u32x4 pack8(f32x4 a, f32x4 b) { u32x4 w; w.x = pk2(a[0], a[1]); w.y = pk2(a[2], a[3]); w.z = pk2(b[0], b[1]); w.w = pk2(b[2], b[3]); return w; }
; __device__ __forceinline__ float sigmoidf_(float x) { return frcp(1.f + fexp2(-x * LOG2E)); }
; __device__ __forceinline__ float siluf_(float x) { return x * sigmoidf_(x); }
;     __device__ __forceinline__ void operator()(const Unit& u, int row, int col, f32x4 v0, f32x4 v1) const {
;         const int g = row >> 11, rowg = row & 2047, j = col >> 4, p = col & 15;
; #pragma unroll
;         for (int i = 0; i < 4; ++i) { v0[i] = gelu_tanh(v0[i]); v1[i] = gelu_tanh(v1[i]); }
;         *(GAS u32x4*)(Y + ((size_t)(rowg * 16 + j) * 512 + g * 16 + p)) = pack8(v0, v1);
	v_fmaak_f32 v53, v42, v53, 0xc0135761
	v_exp_f32_e32 v55, v54
	v_mul_f32_e32 v54, 0xbdd2d3e8, v43
	v_exp_f32_e32 v48, v48
	v_fmaak_f32 v52, v46, v52, 0xc0135761
	v_mul_f32_e32 v53, v42, v53
	v_fmaak_f32 v54, v43, v54, 0xc0135761
	v_mul_f32_e32 v52, v46, v52
	v_mul_f32_e32 v54, v43, v54
	v_add_f32_e32 v48, 1.0, v48
	v_exp_f32_e32 v53, v53
	v_rcp_f32_e32 v48, v48
	v_rcp_f32_e32 v49, v49
	v_exp_f32_e32 v52, v52
	v_exp_f32_e32 v57, v54
	v_rcp_f32_e32 v51, v51
	v_add_f32_e32 v53, 1.0, v53
	v_or_b32_e32 v56, 0x100, v64
	v_add_f32_e32 v52, 1.0, v52
	v_rcp_f32_e32 v54, v53
	v_add_f32_e32 v53, 1.0, v55
	v_add_f32_e32 v55, 1.0, v57
	v_pk_mul_f32 v[44:45], v[44:45], v[48:49]
	v_rcp_f32_e32 v52, v52
	v_rcp_f32_e32 v53, v53
	v_rcp_f32_e32 v55, v55
	v_pk_mul_f32 v[48:49], v[40:41], v[50:51]
	v_cvt_pk_bf16_f32 v40, v44, v45
	v_add_u32_e32 v44, v56, v148
	v_ashrrev_i32_e32 v45, 31, v44
	v_lshlrev_b64 v[44:45], 10, v[44:45]
	v_lshl_add_u64 v[44:45], s[36:37], 0, v[44:45]
	v_pk_mul_f32 v[46:47], v[46:47], v[52:53]
	v_pk_mul_f32 v[50:51], v[42:43], v[54:55]
	v_lshl_add_u64 v[44:45], v[44:45], 0, s[50:51]
	v_cvt_pk_bf16_f32 v41, v46, v47
	v_cvt_pk_bf16_f32 v42, v48, v49
	v_cvt_pk_bf16_f32 v43, v50, v51
	v_lshl_add_u64 v[44:45], v[44:45], 0, v[136:137]
	v_mul_f32_e32 v46, 0xbdd2d3e8, v36
	global_store_dwordx4 v[44:45], v[40:43], off
	v_fmaak_f32 v46, v36, v46, 0xc0135761
	v_mul_f32_e32 v46, v36, v46
	v_mul_f32_e32 v42, 0xbdd2d3e8, v37
	v_fmaak_f32 v42, v37, v42, 0xc0135761
	v_mul_f32_e32 v42, v37, v42
	v_mul_f32_e32 v47, 0xbdd2d3e8, v32
	v_exp_f32_e32 v46, v46
	v_fmaak_f32 v47, v32, v47, 0xc0135761
	v_exp_f32_e32 v43, v42
	v_mul_f32_e32 v42, 0xbdd2d3e8, v33
	v_mul_f32_e32 v47, v32, v47
	v_fmaak_f32 v42, v33, v42, 0xc0135761
	v_mul_f32_e32 v42, v33, v42
	v_add_f32_e32 v40, 1.0, v46
	v_mul_f32_e32 v46, 0xbdd2d3e8, v39
	v_exp_f32_e32 v47, v47
	v_fmaak_f32 v46, v39, v46, 0xc0135761
	v_exp_f32_e32 v44, v42
	v_mul_f32_e32 v46, v39, v46
	v_add_f32_e32 v41, 1.0, v47
	v_mul_f32_e32 v45, 0xbdd2d3e8, v34
	v_rcp_f32_e32 v42, v41
	v_add_f32_e32 v41, 1.0, v43
	v_add_f32_e32 v43, 1.0, v44
	v_mul_f32_e32 v44, 0xbdd2d3e8, v38
	v_fmaak_f32 v45, v34, v45, 0xc0135761
	v_exp_f32_e32 v47, v46
	v_mul_f32_e32 v46, 0xbdd2d3e8, v35
	v_fmaak_f32 v44, v38, v44, 0xc0135761
	v_mul_f32_e32 v45, v34, v45
	v_fmaak_f32 v46, v35, v46, 0xc0135761
	v_mul_f32_e32 v44, v38, v44
	v_mul_f32_e32 v46, v35, v46
	v_exp_f32_e32 v45, v45
	v_rcp_f32_e32 v40, v40
	v_rcp_f32_e32 v41, v41
	v_exp_f32_e32 v44, v44
	v_exp_f32_e32 v48, v46
	v_rcp_f32_e32 v43, v43
	v_add_f32_e32 v45, 1.0, v45
	v_add_f32_e32 v44, 1.0, v44
	v_rcp_f32_e32 v46, v45
	v_add_f32_e32 v45, 1.0, v47
	v_add_f32_e32 v47, 1.0, v48
	v_pk_mul_f32 v[36:37], v[36:37], v[40:41]
	v_rcp_f32_e32 v44, v44
	v_rcp_f32_e32 v45, v45
	v_rcp_f32_e32 v47, v47
	v_pk_mul_f32 v[40:41], v[32:33], v[42:43]
	v_cvt_pk_bf16_f32 v32, v36, v37
	v_add_u32_e32 v36, v56, v149
	v_ashrrev_i32_e32 v37, 31, v36
	v_lshlrev_b64 v[36:37], 10, v[36:37]
	v_lshl_add_u64 v[36:37], s[36:37], 0, v[36:37]
	v_pk_mul_f32 v[38:39], v[38:39], v[44:45]
	v_pk_mul_f32 v[42:43], v[34:35], v[46:47]
	v_lshl_add_u64 v[36:37], v[36:37], 0, s[50:51]
	v_cvt_pk_bf16_f32 v33, v38, v39
	v_cvt_pk_bf16_f32 v34, v40, v41
	v_cvt_pk_bf16_f32 v35, v42, v43
	v_lshl_add_u64 v[36:37], v[36:37], 0, v[136:137]
	global_store_dwordx4 v[36:37], v[32:35], off
	v_mul_f32_e32 v38, 0xbdd2d3e8, v31
	v_fmaak_f32 v38, v31, v38, 0xc0135761
	v_mul_f32_e32 v34, 0xbdd2d3e8, v29
	v_fmaak_f32 v34, v29, v34, 0xc0135761
	v_mul_f32_e32 v34, v29, v34
	v_mul_f32_e32 v33, 0xbdd2d3e8, v24
	v_fmaak_f32 v33, v24, v33, 0xc0135761
	v_exp_f32_e32 v35, v34
	v_mul_f32_e32 v34, 0xbdd2d3e8, v25
	v_mul_f32_e32 v33, v24, v33
	v_fmaak_f32 v34, v25, v34, 0xc0135761
	v_mul_f32_e32 v34, v25, v34
	v_mul_f32_e32 v32, 0xbdd2d3e8, v28
	v_exp_f32_e32 v33, v33
	v_fmaak_f32 v32, v28, v32, 0xc0135761
	v_exp_f32_e32 v36, v34
	v_mul_f32_e32 v38, v31, v38
	v_mul_f32_e32 v32, v28, v32
	v_add_f32_e32 v33, 1.0, v33
	v_mul_f32_e32 v37, 0xbdd2d3e8, v26
	v_rcp_f32_e32 v34, v33
	v_add_f32_e32 v33, 1.0, v35
	v_add_f32_e32 v35, 1.0, v36
	v_mul_f32_e32 v36, 0xbdd2d3e8, v30
	v_fmaak_f32 v37, v26, v37, 0xc0135761
	v_exp_f32_e32 v39, v38
	v_mul_f32_e32 v38, 0xbdd2d3e8, v27
	v_exp_f32_e32 v32, v32
	v_fmaak_f32 v36, v30, v36, 0xc0135761
	v_mul_f32_e32 v37, v26, v37
	v_fmaak_f32 v38, v27, v38, 0xc0135761
	v_mul_f32_e32 v36, v30, v36
	v_mul_f32_e32 v38, v27, v38
	v_add_f32_e32 v32, 1.0, v32
	v_exp_f32_e32 v37, v37
	v_rcp_f32_e32 v32, v32
	v_rcp_f32_e32 v33, v33
	v_exp_f32_e32 v36, v36
	v_exp_f32_e32 v41, v38
	v_rcp_f32_e32 v35, v35
	v_add_f32_e32 v37, 1.0, v37
	v_or_b32_e32 v40, 0x200, v64
	v_add_f32_e32 v36, 1.0, v36
	v_rcp_f32_e32 v38, v37
	v_add_f32_e32 v37, 1.0, v39
	v_add_f32_e32 v39, 1.0, v41
	v_pk_mul_f32 v[28:29], v[28:29], v[32:33]
	v_rcp_f32_e32 v36, v36
	v_rcp_f32_e32 v37, v37
	v_rcp_f32_e32 v39, v39
	v_pk_mul_f32 v[32:33], v[24:25], v[34:35]
	v_cvt_pk_bf16_f32 v24, v28, v29
	v_add_u32_e32 v28, v40, v148
	v_ashrrev_i32_e32 v29, 31, v28
	v_lshlrev_b64 v[28:29], 10, v[28:29]
	v_lshl_add_u64 v[28:29], s[36:37], 0, v[28:29]
	v_pk_mul_f32 v[30:31], v[30:31], v[36:37]
	v_pk_mul_f32 v[34:35], v[26:27], v[38:39]
	v_lshl_add_u64 v[28:29], v[28:29], 0, s[50:51]
	v_cvt_pk_bf16_f32 v25, v30, v31
	v_cvt_pk_bf16_f32 v26, v32, v33
	v_cvt_pk_bf16_f32 v27, v34, v35
	v_lshl_add_u64 v[28:29], v[28:29], 0, v[136:137]
	v_mul_f32_e32 v30, 0xbdd2d3e8, v20
	global_store_dwordx4 v[28:29], v[24:27], off
	v_fmaak_f32 v30, v20, v30, 0xc0135761
	v_mul_f32_e32 v30, v20, v30
	v_mul_f32_e32 v26, 0xbdd2d3e8, v21
	v_fmaak_f32 v26, v21, v26, 0xc0135761
	v_mul_f32_e32 v26, v21, v26
; #define GAS __attribute__((address_space(1)))
; __device__ __forceinline__ float gelu_tanh(float x) { const float u = 0.7978845608028654f * (x + 0.044715f * x * x * x); return x * sigmoidf_(2.f * u); }
; #define PG8_BAR __builtin_amdgcn_s_barrier()
; __device__ __forceinline__ u32x4 pack8(f32x4 a, f32x4 b) { u32x4 w; w.x = pk2(a[0], a[1]); w.y = pk2(a[2], a[3]); w.z = pk2(b[0], b[1]); w.w = pk2(b[2], b[3]); return w; }
; template <class Epi, class Sched>
; __device__ __forceinline__ void gemm_phase(LAS unsigned char* lds, const Gemm g, const Sched& S, const Epi& E, const int wave_) {
;     ...
;         if (wr == 0) PG8_BAR;
;         E(acc, cur, wr, wc, fr, fq);
;         if (!has_next) break;
; #pragma unroll
;         for (int a = 0; a < 2; ++a)
; #pragma unroll
;             for (int b = 0; b < 2; ++b)
; #pragma unroll
;                 for (int m = 0; m < 4; ++m)
; #pragma unroll
;                     for (int n = 0; n < 2; ++n) acc[a][b][m][n] = (f32x4){0.f, 0.f, 0.f, 0.f};
;         cur = nxt; cA = nA; cB = nB; ++ui;
;         if (wr == 1) PG8_BAR;
;     __device__ __forceinline__ void operator()(const Unit& u, int row, int col, f32x4 v0, f32x4 v1) const {
;         const int g = row >> 11, rowg = row & 2047, j = col >> 4, p = col & 15;
; #pragma unroll
;         for (int i = 0; i < 4; ++i) { v0[i] = gelu_tanh(v0[i]); v1[i] = gelu_tanh(v1[i]); }
;         *(GAS u32x4*)(Y + ((size_t)(rowg * 16 + j) * 512 + g * 16 + p)) = pack8(v0, v1);
	v_mul_f32_e32 v31, 0xbdd2d3e8, v16
	v_exp_f32_e32 v30, v30
	v_fmaak_f32 v31, v16, v31, 0xc0135761
	v_exp_f32_e32 v27, v26
	v_mul_f32_e32 v26, 0xbdd2d3e8, v17
	v_mul_f32_e32 v31, v16, v31
	v_fmaak_f32 v26, v17, v26, 0xc0135761
	v_mul_f32_e32 v26, v17, v26
	v_add_f32_e32 v24, 1.0, v30
	v_mul_f32_e32 v30, 0xbdd2d3e8, v23
	v_exp_f32_e32 v31, v31
	v_fmaak_f32 v30, v23, v30, 0xc0135761
	v_exp_f32_e32 v28, v26
	v_mul_f32_e32 v30, v23, v30
	v_add_f32_e32 v25, 1.0, v31
	v_mul_f32_e32 v29, 0xbdd2d3e8, v18
	v_rcp_f32_e32 v26, v25
	v_add_f32_e32 v25, 1.0, v27
	v_add_f32_e32 v27, 1.0, v28
	v_mul_f32_e32 v28, 0xbdd2d3e8, v22
	v_fmaak_f32 v29, v18, v29, 0xc0135761
	v_exp_f32_e32 v31, v30
	v_mul_f32_e32 v30, 0xbdd2d3e8, v19
	v_fmaak_f32 v28, v22, v28, 0xc0135761
	v_mul_f32_e32 v29, v18, v29
	v_fmaak_f32 v30, v19, v30, 0xc0135761
	v_mul_f32_e32 v28, v22, v28
	v_mul_f32_e32 v30, v19, v30
	v_exp_f32_e32 v29, v29
	v_rcp_f32_e32 v24, v24
	v_rcp_f32_e32 v25, v25
	v_exp_f32_e32 v28, v28
	v_exp_f32_e32 v32, v30
	v_rcp_f32_e32 v27, v27
	v_add_f32_e32 v29, 1.0, v29
	v_add_f32_e32 v28, 1.0, v28
	v_rcp_f32_e32 v30, v29
	v_add_f32_e32 v29, 1.0, v31
	v_add_f32_e32 v31, 1.0, v32
	v_pk_mul_f32 v[20:21], v[20:21], v[24:25]
	v_rcp_f32_e32 v28, v28
	v_rcp_f32_e32 v29, v29
	v_rcp_f32_e32 v31, v31
	v_pk_mul_f32 v[24:25], v[16:17], v[26:27]
	v_cvt_pk_bf16_f32 v16, v20, v21
	v_add_u32_e32 v20, v40, v149
	v_ashrrev_i32_e32 v21, 31, v20
	v_lshlrev_b64 v[20:21], 10, v[20:21]
	v_lshl_add_u64 v[20:21], s[36:37], 0, v[20:21]
	v_pk_mul_f32 v[22:23], v[22:23], v[28:29]
	v_pk_mul_f32 v[26:27], v[18:19], v[30:31]
	v_lshl_add_u64 v[20:21], v[20:21], 0, s[50:51]
	v_cvt_pk_bf16_f32 v17, v22, v23
	v_cvt_pk_bf16_f32 v18, v24, v25
	v_cvt_pk_bf16_f32 v19, v26, v27
	v_lshl_add_u64 v[20:21], v[20:21], 0, v[136:137]
	global_store_dwordx4 v[20:21], v[16:19], off
	v_mul_f32_e32 v22, 0xbdd2d3e8, v15
	v_fmaak_f32 v22, v15, v22, 0xc0135761
	v_mul_f32_e32 v18, 0xbdd2d3e8, v13
	v_fmaak_f32 v18, v13, v18, 0xc0135761
	v_mul_f32_e32 v18, v13, v18
	v_mul_f32_e32 v17, 0xbdd2d3e8, v8
	v_fmaak_f32 v17, v8, v17, 0xc0135761
	v_exp_f32_e32 v19, v18
	v_mul_f32_e32 v18, 0xbdd2d3e8, v9
	v_mul_f32_e32 v17, v8, v17
	v_fmaak_f32 v18, v9, v18, 0xc0135761
	v_mul_f32_e32 v18, v9, v18
	v_mul_f32_e32 v16, 0xbdd2d3e8, v12
	v_exp_f32_e32 v17, v17
	v_fmaak_f32 v16, v12, v16, 0xc0135761
	v_exp_f32_e32 v20, v18
	v_mul_f32_e32 v22, v15, v22
	v_mul_f32_e32 v16, v12, v16
	v_add_f32_e32 v17, 1.0, v17
	v_mul_f32_e32 v21, 0xbdd2d3e8, v10
	v_rcp_f32_e32 v18, v17
	v_add_f32_e32 v17, 1.0, v19
	v_add_f32_e32 v19, 1.0, v20
	v_mul_f32_e32 v20, 0xbdd2d3e8, v14
	v_fmaak_f32 v21, v10, v21, 0xc0135761
	v_exp_f32_e32 v23, v22
	v_mul_f32_e32 v22, 0xbdd2d3e8, v11
	v_exp_f32_e32 v16, v16
	v_fmaak_f32 v20, v14, v20, 0xc0135761
	v_mul_f32_e32 v21, v10, v21
	v_fmaak_f32 v22, v11, v22, 0xc0135761
	v_mul_f32_e32 v20, v14, v20
	v_mul_f32_e32 v22, v11, v22
	v_add_f32_e32 v16, 1.0, v16
	v_exp_f32_e32 v21, v21
	v_rcp_f32_e32 v16, v16
	v_rcp_f32_e32 v17, v17
	v_exp_f32_e32 v20, v20
	v_exp_f32_e32 v25, v22
	v_rcp_f32_e32 v19, v19
	v_add_f32_e32 v21, 1.0, v21
	v_or_b32_e32 v24, 0x300, v64
	v_add_f32_e32 v20, 1.0, v20
	v_rcp_f32_e32 v22, v21
	v_add_f32_e32 v21, 1.0, v23
	v_add_f32_e32 v23, 1.0, v25
	v_pk_mul_f32 v[12:13], v[12:13], v[16:17]
	v_rcp_f32_e32 v20, v20
	v_rcp_f32_e32 v21, v21
	v_rcp_f32_e32 v23, v23
	v_pk_mul_f32 v[16:17], v[8:9], v[18:19]
	v_cvt_pk_bf16_f32 v8, v12, v13
	v_add_u32_e32 v12, v24, v148
	v_ashrrev_i32_e32 v13, 31, v12
	v_lshlrev_b64 v[12:13], 10, v[12:13]
	v_lshl_add_u64 v[12:13], s[36:37], 0, v[12:13]
	v_pk_mul_f32 v[14:15], v[14:15], v[20:21]
	v_pk_mul_f32 v[18:19], v[10:11], v[22:23]
	v_lshl_add_u64 v[12:13], v[12:13], 0, s[50:51]
	v_cvt_pk_bf16_f32 v9, v14, v15
	v_cvt_pk_bf16_f32 v10, v16, v17
	v_cvt_pk_bf16_f32 v11, v18, v19
	v_lshl_add_u64 v[12:13], v[12:13], 0, v[136:137]
	v_mul_f32_e32 v14, 0xbdd2d3e8, v4
	global_store_dwordx4 v[12:13], v[8:11], off
	v_fmaak_f32 v14, v4, v14, 0xc0135761
	v_mul_f32_e32 v14, v4, v14
	v_mul_f32_e32 v10, 0xbdd2d3e8, v5
	v_fmaak_f32 v10, v5, v10, 0xc0135761
	v_mul_f32_e32 v10, v5, v10
	v_mul_f32_e32 v15, 0xbdd2d3e8, v0
	v_exp_f32_e32 v14, v14
	v_fmaak_f32 v15, v0, v15, 0xc0135761
	v_exp_f32_e32 v11, v10
	v_mul_f32_e32 v10, 0xbdd2d3e8, v1
	v_mul_f32_e32 v15, v0, v15
	v_fmaak_f32 v10, v1, v10, 0xc0135761
	v_mul_f32_e32 v10, v1, v10
	v_add_f32_e32 v8, 1.0, v14
	v_mul_f32_e32 v14, 0xbdd2d3e8, v7
	v_exp_f32_e32 v15, v15
	v_fmaak_f32 v14, v7, v14, 0xc0135761
	v_exp_f32_e32 v12, v10
	v_mul_f32_e32 v14, v7, v14
	v_add_f32_e32 v9, 1.0, v15
	v_mul_f32_e32 v13, 0xbdd2d3e8, v2
	v_rcp_f32_e32 v10, v9
	v_add_f32_e32 v9, 1.0, v11
	v_add_f32_e32 v11, 1.0, v12
	v_mul_f32_e32 v12, 0xbdd2d3e8, v6
	v_fmaak_f32 v13, v2, v13, 0xc0135761
	v_exp_f32_e32 v15, v14
	v_mul_f32_e32 v14, 0xbdd2d3e8, v3
	v_fmaak_f32 v12, v6, v12, 0xc0135761
	v_mul_f32_e32 v13, v2, v13
	v_fmaak_f32 v14, v3, v14, 0xc0135761
	v_mul_f32_e32 v12, v6, v12
	v_mul_f32_e32 v14, v3, v14
	v_exp_f32_e32 v13, v13
	v_rcp_f32_e32 v8, v8
	v_rcp_f32_e32 v9, v9
	v_exp_f32_e32 v12, v12
	v_exp_f32_e32 v16, v14
	v_rcp_f32_e32 v11, v11
	v_add_f32_e32 v13, 1.0, v13
	v_add_f32_e32 v12, 1.0, v12
	v_rcp_f32_e32 v14, v13
	v_add_f32_e32 v13, 1.0, v15
	v_add_f32_e32 v15, 1.0, v16
	v_pk_mul_f32 v[4:5], v[4:5], v[8:9]
	v_rcp_f32_e32 v12, v12
	v_rcp_f32_e32 v13, v13
	v_rcp_f32_e32 v15, v15
	v_pk_mul_f32 v[8:9], v[0:1], v[10:11]
	v_cvt_pk_bf16_f32 v0, v4, v5
	v_add_u32_e32 v4, v24, v149
	v_ashrrev_i32_e32 v5, 31, v4
	v_lshlrev_b64 v[4:5], 10, v[4:5]
	v_lshl_add_u64 v[4:5], s[36:37], 0, v[4:5]
	v_pk_mul_f32 v[6:7], v[6:7], v[12:13]
	v_pk_mul_f32 v[10:11], v[2:3], v[14:15]
	v_lshl_add_u64 v[4:5], v[4:5], 0, s[50:51]
	v_cvt_pk_bf16_f32 v1, v6, v7
	v_cvt_pk_bf16_f32 v2, v8, v9
	v_cvt_pk_bf16_f32 v3, v10, v11
	v_lshl_add_u64 v[4:5], v[4:5], 0, v[136:137]
	s_andn2_b64 vcc, exec, s[8:9]
	s_mov_b64 s[8:9], -1
	global_store_dwordx4 v[4:5], v[0:3], off
	s_cbranch_vccnz .LBB0_691
	s_andn2_b64 vcc, exec, s[34:35]
	s_cbranch_vccnz .LBB0_690
	s_barrier
	s_branch .LBB0_690
